# EpiResid epilogues rewritten: 16 residual loads hoisted, counted vmcnt, batched bpermute
# speedup vs baseline: 1.0097x; 1.0097x over previous
.LBB0_761:
	v_lshl_add_u32 v142, s24, 8, v144
	v_lshl_or_b32 v140, s22, 8, v146
	v_lshlrev_b32_e32 v141, 1, v140
	v_lshl_add_u32 v188, v142, 11, v141
	s_lshl_b32 s22, s22, 2
	s_ashr_i32 s23, s22, 31
	global_load_dwordx4 v[148:151], v188, s[6:7]
	global_load_dwordx4 v[152:155], v188, s[6:7] offset:256
	v_add_u32_e32 v189, 0x8000, v188
	global_load_dwordx4 v[156:159], v189, s[6:7]
	global_load_dwordx4 v[160:163], v189, s[6:7] offset:256
	v_add_u32_e32 v189, 0x10000, v188
	global_load_dwordx4 v[164:167], v189, s[6:7]
	global_load_dwordx4 v[168:171], v189, s[6:7] offset:256
	v_add_u32_e32 v189, 0x18000, v188
	global_load_dwordx4 v[172:175], v189, s[6:7]
	global_load_dwordx4 v[176:179], v189, s[6:7] offset:256
	v_add_u32_e32 v189, 0x40000, v188
	global_load_dwordx4 v[180:183], v189, s[6:7]
	global_load_dwordx4 v[184:187], v189, s[6:7] offset:256
	v_add_u32_e32 v189, 0x48000, v188
	global_load_dwordx4 v[208:211], v189, s[6:7]
	global_load_dwordx4 v[230:233], v189, s[6:7] offset:256
	v_add_u32_e32 v189, 0x50000, v188
	global_load_dwordx4 v[234:237], v189, s[6:7]
	global_load_dwordx4 v[238:241], v189, s[6:7] offset:256
	v_add_u32_e32 v189, 0x58000, v188
	global_load_dwordx4 v[242:245], v189, s[6:7]
	global_load_dwordx4 v[246:249], v189, s[6:7] offset:256
	s_waitcnt vmcnt(14)
	v_lshlrev_b32_e32 v140, 16, v148
	v_and_b32_e32 v148, 0xffff0000, v148
	v_lshlrev_b32_e32 v141, 16, v149
	v_and_b32_e32 v149, 0xffff0000, v149
	v_lshlrev_b32_e32 v142, 16, v150
	v_and_b32_e32 v150, 0xffff0000, v150
	v_lshlrev_b32_e32 v143, 16, v151
	v_and_b32_e32 v151, 0xffff0000, v151
	v_add_f32_e32 v140, v126, v140
	v_add_f32_e32 v148, v127, v148
	v_add_f32_e32 v141, v128, v141
	v_add_f32_e32 v149, v129, v149
	v_add_f32_e32 v142, v122, v142
	v_add_f32_e32 v150, v123, v150
	v_add_f32_e32 v143, v124, v143
	v_add_f32_e32 v151, v125, v151
	v_mul_f32_e32 v126, v140, v140
	v_fmac_f32_e32 v126, v148, v148
	v_fmac_f32_e32 v126, v141, v141
	v_fmac_f32_e32 v126, v149, v149
	v_fmac_f32_e32 v126, v142, v142
	v_fmac_f32_e32 v126, v150, v150
	v_fmac_f32_e32 v126, v143, v143
	v_fmac_f32_e32 v126, v151, v151
	v_cvt_pk_bf16_f32 v148, v140, v148
	v_cvt_pk_bf16_f32 v149, v141, v149
	v_cvt_pk_bf16_f32 v150, v142, v150
	v_cvt_pk_bf16_f32 v151, v143, v151
	global_store_dwordx4 v188, v[148:151], s[6:7]
	v_lshlrev_b32_e32 v140, 16, v152
	v_and_b32_e32 v152, 0xffff0000, v152
	v_lshlrev_b32_e32 v141, 16, v153
	v_and_b32_e32 v153, 0xffff0000, v153
	v_lshlrev_b32_e32 v142, 16, v154
	v_and_b32_e32 v154, 0xffff0000, v154
	v_lshlrev_b32_e32 v143, 16, v155
	v_and_b32_e32 v155, 0xffff0000, v155
	v_add_f32_e32 v140, v118, v140
	v_add_f32_e32 v152, v119, v152
	v_add_f32_e32 v141, v120, v141
	v_add_f32_e32 v153, v121, v153
	v_add_f32_e32 v142, v114, v142
	v_add_f32_e32 v154, v115, v154
	v_add_f32_e32 v143, v116, v143
	v_add_f32_e32 v155, v117, v155
	v_fmac_f32_e32 v126, v140, v140
	v_fmac_f32_e32 v126, v152, v152
	v_fmac_f32_e32 v126, v141, v141
	v_fmac_f32_e32 v126, v153, v153
	v_fmac_f32_e32 v126, v142, v142
	v_fmac_f32_e32 v126, v154, v154
	v_fmac_f32_e32 v126, v143, v143
	v_fmac_f32_e32 v126, v155, v155
	v_cvt_pk_bf16_f32 v152, v140, v152
	v_cvt_pk_bf16_f32 v153, v141, v153
	v_cvt_pk_bf16_f32 v154, v142, v154
	v_cvt_pk_bf16_f32 v155, v143, v155
	global_store_dwordx4 v188, v[152:155], s[6:7] offset:256
	s_waitcnt vmcnt(14)
	v_add_u32_e32 v189, 0x8000, v188
	v_lshlrev_b32_e32 v140, 16, v156
	v_and_b32_e32 v156, 0xffff0000, v156
	v_lshlrev_b32_e32 v141, 16, v157
	v_and_b32_e32 v157, 0xffff0000, v157
	v_lshlrev_b32_e32 v142, 16, v158
	v_and_b32_e32 v158, 0xffff0000, v158
	v_lshlrev_b32_e32 v143, 16, v159
	v_and_b32_e32 v159, 0xffff0000, v159
	v_add_f32_e32 v140, v108, v140
	v_add_f32_e32 v156, v109, v156
	v_add_f32_e32 v141, v110, v141
	v_add_f32_e32 v157, v111, v157
	v_add_f32_e32 v142, v104, v142
	v_add_f32_e32 v158, v105, v158
	v_add_f32_e32 v143, v106, v143
	v_add_f32_e32 v159, v107, v159
	v_mul_f32_e32 v108, v140, v140
	v_fmac_f32_e32 v108, v156, v156
	v_fmac_f32_e32 v108, v141, v141
	v_fmac_f32_e32 v108, v157, v157
	v_fmac_f32_e32 v108, v142, v142
	v_fmac_f32_e32 v108, v158, v158
	v_fmac_f32_e32 v108, v143, v143
	v_fmac_f32_e32 v108, v159, v159
	v_cvt_pk_bf16_f32 v156, v140, v156
	v_cvt_pk_bf16_f32 v157, v141, v157
	v_cvt_pk_bf16_f32 v158, v142, v158
	v_cvt_pk_bf16_f32 v159, v143, v159
	global_store_dwordx4 v189, v[156:159], s[6:7]
	v_lshlrev_b32_e32 v140, 16, v160
	v_and_b32_e32 v160, 0xffff0000, v160
	v_lshlrev_b32_e32 v141, 16, v161
	v_and_b32_e32 v161, 0xffff0000, v161
	v_lshlrev_b32_e32 v142, 16, v162
	v_and_b32_e32 v162, 0xffff0000, v162
	v_lshlrev_b32_e32 v143, 16, v163
	v_and_b32_e32 v163, 0xffff0000, v163
	v_add_f32_e32 v140, v100, v140
	v_add_f32_e32 v160, v101, v160
	v_add_f32_e32 v141, v102, v141
	v_add_f32_e32 v161, v103, v161
	v_add_f32_e32 v142, v96, v142
	v_add_f32_e32 v162, v97, v162
	v_add_f32_e32 v143, v98, v143
	v_add_f32_e32 v163, v99, v163
	v_fmac_f32_e32 v108, v140, v140
	v_fmac_f32_e32 v108, v160, v160
	v_fmac_f32_e32 v108, v141, v141
	v_fmac_f32_e32 v108, v161, v161
	v_fmac_f32_e32 v108, v142, v142
	v_fmac_f32_e32 v108, v162, v162
	v_fmac_f32_e32 v108, v143, v143
	v_fmac_f32_e32 v108, v163, v163
	v_cvt_pk_bf16_f32 v160, v140, v160
	v_cvt_pk_bf16_f32 v161, v141, v161
	v_cvt_pk_bf16_f32 v162, v142, v162
	v_cvt_pk_bf16_f32 v163, v143, v163
	global_store_dwordx4 v189, v[160:163], s[6:7] offset:256
	s_waitcnt vmcnt(14)
	v_add_u32_e32 v189, 0x10000, v188
	v_lshlrev_b32_e32 v140, 16, v164
	v_and_b32_e32 v164, 0xffff0000, v164
	v_lshlrev_b32_e32 v141, 16, v165
	v_and_b32_e32 v165, 0xffff0000, v165
	v_lshlrev_b32_e32 v142, 16, v166
	v_and_b32_e32 v166, 0xffff0000, v166
	v_lshlrev_b32_e32 v143, 16, v167
	v_and_b32_e32 v167, 0xffff0000, v167
	v_add_f32_e32 v140, v92, v140
	v_add_f32_e32 v164, v93, v164
	v_add_f32_e32 v141, v94, v141
	v_add_f32_e32 v165, v95, v165
	v_add_f32_e32 v142, v88, v142
	v_add_f32_e32 v166, v89, v166
	v_add_f32_e32 v143, v90, v143
	v_add_f32_e32 v167, v91, v167
	v_mul_f32_e32 v92, v140, v140
	v_fmac_f32_e32 v92, v164, v164
	v_fmac_f32_e32 v92, v141, v141
	v_fmac_f32_e32 v92, v165, v165
	v_fmac_f32_e32 v92, v142, v142
	v_fmac_f32_e32 v92, v166, v166
	v_fmac_f32_e32 v92, v143, v143
	v_fmac_f32_e32 v92, v167, v167
	v_cvt_pk_bf16_f32 v164, v140, v164
	v_cvt_pk_bf16_f32 v165, v141, v165
	v_cvt_pk_bf16_f32 v166, v142, v166
	v_cvt_pk_bf16_f32 v167, v143, v167
	global_store_dwordx4 v189, v[164:167], s[6:7]
	v_lshlrev_b32_e32 v140, 16, v168
	v_and_b32_e32 v168, 0xffff0000, v168
	v_lshlrev_b32_e32 v141, 16, v169
	v_and_b32_e32 v169, 0xffff0000, v169
	v_lshlrev_b32_e32 v142, 16, v170
	v_and_b32_e32 v170, 0xffff0000, v170
	v_lshlrev_b32_e32 v143, 16, v171
	v_and_b32_e32 v171, 0xffff0000, v171
	v_add_f32_e32 v140, v84, v140
	v_add_f32_e32 v168, v85, v168
	v_add_f32_e32 v141, v86, v141
	v_add_f32_e32 v169, v87, v169
	v_add_f32_e32 v142, v80, v142
	v_add_f32_e32 v170, v81, v170
	v_add_f32_e32 v143, v82, v143
	v_add_f32_e32 v171, v83, v171
	v_fmac_f32_e32 v92, v140, v140
	v_fmac_f32_e32 v92, v168, v168
	v_fmac_f32_e32 v92, v141, v141
	v_fmac_f32_e32 v92, v169, v169
	v_fmac_f32_e32 v92, v142, v142
	v_fmac_f32_e32 v92, v170, v170
	v_fmac_f32_e32 v92, v143, v143
	v_fmac_f32_e32 v92, v171, v171
	v_cvt_pk_bf16_f32 v168, v140, v168
	v_cvt_pk_bf16_f32 v169, v141, v169
	v_cvt_pk_bf16_f32 v170, v142, v170
	v_cvt_pk_bf16_f32 v171, v143, v171
	global_store_dwordx4 v189, v[168:171], s[6:7] offset:256
	s_waitcnt vmcnt(14)
	v_add_u32_e32 v189, 0x18000, v188
	v_lshlrev_b32_e32 v140, 16, v172
	v_and_b32_e32 v172, 0xffff0000, v172
	v_lshlrev_b32_e32 v141, 16, v173
	v_and_b32_e32 v173, 0xffff0000, v173
	v_lshlrev_b32_e32 v142, 16, v174
	v_and_b32_e32 v174, 0xffff0000, v174
	v_lshlrev_b32_e32 v143, 16, v175
	v_and_b32_e32 v175, 0xffff0000, v175
	v_add_f32_e32 v140, v76, v140
	v_add_f32_e32 v172, v77, v172
	v_add_f32_e32 v141, v78, v141
	v_add_f32_e32 v173, v79, v173
	v_add_f32_e32 v142, v72, v142
	v_add_f32_e32 v174, v73, v174
	v_add_f32_e32 v143, v74, v143
	v_add_f32_e32 v175, v75, v175
	v_mul_f32_e32 v76, v140, v140
	v_fmac_f32_e32 v76, v172, v172
	v_fmac_f32_e32 v76, v141, v141
	v_fmac_f32_e32 v76, v173, v173
	v_fmac_f32_e32 v76, v142, v142
	v_fmac_f32_e32 v76, v174, v174
	v_fmac_f32_e32 v76, v143, v143
	v_fmac_f32_e32 v76, v175, v175
	v_cvt_pk_bf16_f32 v172, v140, v172
	v_cvt_pk_bf16_f32 v173, v141, v173
	v_cvt_pk_bf16_f32 v174, v142, v174
	v_cvt_pk_bf16_f32 v175, v143, v175
	global_store_dwordx4 v189, v[172:175], s[6:7]
	v_lshlrev_b32_e32 v140, 16, v176
	v_and_b32_e32 v176, 0xffff0000, v176
	v_lshlrev_b32_e32 v141, 16, v177
	v_and_b32_e32 v177, 0xffff0000, v177
	v_lshlrev_b32_e32 v142, 16, v178
	v_and_b32_e32 v178, 0xffff0000, v178
	v_lshlrev_b32_e32 v143, 16, v179
	v_and_b32_e32 v179, 0xffff0000, v179
	v_add_f32_e32 v140, v68, v140
	v_add_f32_e32 v176, v69, v176
	v_add_f32_e32 v141, v70, v141
	v_add_f32_e32 v177, v71, v177
	v_add_f32_e32 v142, v64, v142
	v_add_f32_e32 v178, v65, v178
	v_add_f32_e32 v143, v66, v143
	v_add_f32_e32 v179, v67, v179
	v_fmac_f32_e32 v76, v140, v140
	v_fmac_f32_e32 v76, v176, v176
	v_fmac_f32_e32 v76, v141, v141
	v_fmac_f32_e32 v76, v177, v177
	v_fmac_f32_e32 v76, v142, v142
	v_fmac_f32_e32 v76, v178, v178
	v_fmac_f32_e32 v76, v143, v143
	v_fmac_f32_e32 v76, v179, v179
	v_cvt_pk_bf16_f32 v176, v140, v176
	v_cvt_pk_bf16_f32 v177, v141, v177
	v_cvt_pk_bf16_f32 v178, v142, v178
	v_cvt_pk_bf16_f32 v179, v143, v179
	global_store_dwordx4 v189, v[176:179], s[6:7] offset:256
	s_waitcnt vmcnt(14)
	v_add_u32_e32 v189, 0x40000, v188
	v_lshlrev_b32_e32 v140, 16, v180
	v_and_b32_e32 v180, 0xffff0000, v180
	v_lshlrev_b32_e32 v141, 16, v181
	v_and_b32_e32 v181, 0xffff0000, v181
	v_lshlrev_b32_e32 v142, 16, v182
	v_and_b32_e32 v182, 0xffff0000, v182
	v_lshlrev_b32_e32 v143, 16, v183
	v_and_b32_e32 v183, 0xffff0000, v183
	v_add_f32_e32 v140, v60, v140
	v_add_f32_e32 v180, v61, v180
	v_add_f32_e32 v141, v62, v141
	v_add_f32_e32 v181, v63, v181
	v_add_f32_e32 v142, v56, v142
	v_add_f32_e32 v182, v57, v182
	v_add_f32_e32 v143, v58, v143
	v_add_f32_e32 v183, v59, v183
	v_mul_f32_e32 v60, v140, v140
	v_fmac_f32_e32 v60, v180, v180
	v_fmac_f32_e32 v60, v141, v141
	v_fmac_f32_e32 v60, v181, v181
	v_fmac_f32_e32 v60, v142, v142
	v_fmac_f32_e32 v60, v182, v182
	v_fmac_f32_e32 v60, v143, v143
	v_fmac_f32_e32 v60, v183, v183
	v_cvt_pk_bf16_f32 v180, v140, v180
	v_cvt_pk_bf16_f32 v181, v141, v181
	v_cvt_pk_bf16_f32 v182, v142, v182
	v_cvt_pk_bf16_f32 v183, v143, v183
	global_store_dwordx4 v189, v[180:183], s[6:7]
	v_lshlrev_b32_e32 v140, 16, v184
	v_and_b32_e32 v184, 0xffff0000, v184
	v_lshlrev_b32_e32 v141, 16, v185
	v_and_b32_e32 v185, 0xffff0000, v185
	v_lshlrev_b32_e32 v142, 16, v186
	v_and_b32_e32 v186, 0xffff0000, v186
	v_lshlrev_b32_e32 v143, 16, v187
	v_and_b32_e32 v187, 0xffff0000, v187
	v_add_f32_e32 v140, v52, v140
	v_add_f32_e32 v184, v53, v184
	v_add_f32_e32 v141, v54, v141
	v_add_f32_e32 v185, v55, v185
	v_add_f32_e32 v142, v48, v142
	v_add_f32_e32 v186, v49, v186
	v_add_f32_e32 v143, v50, v143
	v_add_f32_e32 v187, v51, v187
	v_fmac_f32_e32 v60, v140, v140
	v_fmac_f32_e32 v60, v184, v184
	v_fmac_f32_e32 v60, v141, v141
	v_fmac_f32_e32 v60, v185, v185
	v_fmac_f32_e32 v60, v142, v142
	v_fmac_f32_e32 v60, v186, v186
	v_fmac_f32_e32 v60, v143, v143
	v_fmac_f32_e32 v60, v187, v187
	v_cvt_pk_bf16_f32 v184, v140, v184
	v_cvt_pk_bf16_f32 v185, v141, v185
	v_cvt_pk_bf16_f32 v186, v142, v186
	v_cvt_pk_bf16_f32 v187, v143, v187
	global_store_dwordx4 v189, v[184:187], s[6:7] offset:256
	s_waitcnt vmcnt(14)
	v_add_u32_e32 v189, 0x48000, v188
	v_lshlrev_b32_e32 v140, 16, v208
	v_and_b32_e32 v208, 0xffff0000, v208
	v_lshlrev_b32_e32 v141, 16, v209
	v_and_b32_e32 v209, 0xffff0000, v209
	v_lshlrev_b32_e32 v142, 16, v210
	v_and_b32_e32 v210, 0xffff0000, v210
	v_lshlrev_b32_e32 v143, 16, v211
	v_and_b32_e32 v211, 0xffff0000, v211
	v_add_f32_e32 v140, v44, v140
	v_add_f32_e32 v208, v45, v208
	v_add_f32_e32 v141, v46, v141
	v_add_f32_e32 v209, v47, v209
	v_add_f32_e32 v142, v40, v142
	v_add_f32_e32 v210, v41, v210
	v_add_f32_e32 v143, v42, v143
	v_add_f32_e32 v211, v43, v211
	v_mul_f32_e32 v44, v140, v140
	v_fmac_f32_e32 v44, v208, v208
	v_fmac_f32_e32 v44, v141, v141
	v_fmac_f32_e32 v44, v209, v209
	v_fmac_f32_e32 v44, v142, v142
	v_fmac_f32_e32 v44, v210, v210
	v_fmac_f32_e32 v44, v143, v143
	v_fmac_f32_e32 v44, v211, v211
	v_cvt_pk_bf16_f32 v208, v140, v208
	v_cvt_pk_bf16_f32 v209, v141, v209
	v_cvt_pk_bf16_f32 v210, v142, v210
	v_cvt_pk_bf16_f32 v211, v143, v211
	global_store_dwordx4 v189, v[208:211], s[6:7]
	v_lshlrev_b32_e32 v140, 16, v230
	v_and_b32_e32 v230, 0xffff0000, v230
	v_lshlrev_b32_e32 v141, 16, v231
	v_and_b32_e32 v231, 0xffff0000, v231
	v_lshlrev_b32_e32 v142, 16, v232
	v_and_b32_e32 v232, 0xffff0000, v232
	v_lshlrev_b32_e32 v143, 16, v233
	v_and_b32_e32 v233, 0xffff0000, v233
	v_add_f32_e32 v140, v36, v140
	v_add_f32_e32 v230, v37, v230
	v_add_f32_e32 v141, v38, v141
	v_add_f32_e32 v231, v39, v231
	v_add_f32_e32 v142, v32, v142
	v_add_f32_e32 v232, v33, v232
	v_add_f32_e32 v143, v34, v143
	v_add_f32_e32 v233, v35, v233
	v_fmac_f32_e32 v44, v140, v140
	v_fmac_f32_e32 v44, v230, v230
	v_fmac_f32_e32 v44, v141, v141
	v_fmac_f32_e32 v44, v231, v231
	v_fmac_f32_e32 v44, v142, v142
	v_fmac_f32_e32 v44, v232, v232
	v_fmac_f32_e32 v44, v143, v143
	v_fmac_f32_e32 v44, v233, v233
	v_cvt_pk_bf16_f32 v230, v140, v230
	v_cvt_pk_bf16_f32 v231, v141, v231
	v_cvt_pk_bf16_f32 v232, v142, v232
	v_cvt_pk_bf16_f32 v233, v143, v233
	global_store_dwordx4 v189, v[230:233], s[6:7] offset:256
	s_waitcnt vmcnt(14)
	v_add_u32_e32 v189, 0x50000, v188
	v_lshlrev_b32_e32 v140, 16, v234
	v_and_b32_e32 v234, 0xffff0000, v234
	v_lshlrev_b32_e32 v141, 16, v235
	v_and_b32_e32 v235, 0xffff0000, v235
	v_lshlrev_b32_e32 v142, 16, v236
	v_and_b32_e32 v236, 0xffff0000, v236
	v_lshlrev_b32_e32 v143, 16, v237
	v_and_b32_e32 v237, 0xffff0000, v237
	v_add_f32_e32 v140, v28, v140
	v_add_f32_e32 v234, v29, v234
	v_add_f32_e32 v141, v30, v141
	v_add_f32_e32 v235, v31, v235
	v_add_f32_e32 v142, v24, v142
	v_add_f32_e32 v236, v25, v236
	v_add_f32_e32 v143, v26, v143
	v_add_f32_e32 v237, v27, v237
	v_mul_f32_e32 v28, v140, v140
	v_fmac_f32_e32 v28, v234, v234
	v_fmac_f32_e32 v28, v141, v141
	v_fmac_f32_e32 v28, v235, v235
	v_fmac_f32_e32 v28, v142, v142
	v_fmac_f32_e32 v28, v236, v236
	v_fmac_f32_e32 v28, v143, v143
	v_fmac_f32_e32 v28, v237, v237
	v_cvt_pk_bf16_f32 v234, v140, v234
	v_cvt_pk_bf16_f32 v235, v141, v235
	v_cvt_pk_bf16_f32 v236, v142, v236
	v_cvt_pk_bf16_f32 v237, v143, v237
	global_store_dwordx4 v189, v[234:237], s[6:7]
	v_lshlrev_b32_e32 v140, 16, v238
	v_and_b32_e32 v238, 0xffff0000, v238
	v_lshlrev_b32_e32 v141, 16, v239
	v_and_b32_e32 v239, 0xffff0000, v239
	v_lshlrev_b32_e32 v142, 16, v240
	v_and_b32_e32 v240, 0xffff0000, v240
	v_lshlrev_b32_e32 v143, 16, v241
	v_and_b32_e32 v241, 0xffff0000, v241
	v_add_f32_e32 v140, v20, v140
	v_add_f32_e32 v238, v21, v238
	v_add_f32_e32 v141, v22, v141
	v_add_f32_e32 v239, v23, v239
	v_add_f32_e32 v142, v16, v142
	v_add_f32_e32 v240, v17, v240
	v_add_f32_e32 v143, v18, v143
	v_add_f32_e32 v241, v19, v241
	v_fmac_f32_e32 v28, v140, v140
	v_fmac_f32_e32 v28, v238, v238
	v_fmac_f32_e32 v28, v141, v141
	v_fmac_f32_e32 v28, v239, v239
	v_fmac_f32_e32 v28, v142, v142
	v_fmac_f32_e32 v28, v240, v240
	v_fmac_f32_e32 v28, v143, v143
	v_fmac_f32_e32 v28, v241, v241
	v_cvt_pk_bf16_f32 v238, v140, v238
	v_cvt_pk_bf16_f32 v239, v141, v239
	v_cvt_pk_bf16_f32 v240, v142, v240
	v_cvt_pk_bf16_f32 v241, v143, v241
	global_store_dwordx4 v189, v[238:241], s[6:7] offset:256
	s_waitcnt vmcnt(14)
	v_add_u32_e32 v189, 0x58000, v188
	v_lshlrev_b32_e32 v140, 16, v242
	v_and_b32_e32 v242, 0xffff0000, v242
	v_lshlrev_b32_e32 v141, 16, v243
	v_and_b32_e32 v243, 0xffff0000, v243
	v_lshlrev_b32_e32 v142, 16, v244
	v_and_b32_e32 v244, 0xffff0000, v244
	v_lshlrev_b32_e32 v143, 16, v245
	v_and_b32_e32 v245, 0xffff0000, v245
	v_add_f32_e32 v140, v12, v140
	v_add_f32_e32 v242, v13, v242
	v_add_f32_e32 v141, v14, v141
	v_add_f32_e32 v243, v15, v243
	v_add_f32_e32 v142, v8, v142
	v_add_f32_e32 v244, v9, v244
	v_add_f32_e32 v143, v10, v143
	v_add_f32_e32 v245, v11, v245
	v_mul_f32_e32 v12, v140, v140
	v_fmac_f32_e32 v12, v242, v242
	v_fmac_f32_e32 v12, v141, v141
	v_fmac_f32_e32 v12, v243, v243
	v_fmac_f32_e32 v12, v142, v142
	v_fmac_f32_e32 v12, v244, v244
	v_fmac_f32_e32 v12, v143, v143
	v_fmac_f32_e32 v12, v245, v245
	v_cvt_pk_bf16_f32 v242, v140, v242
	v_cvt_pk_bf16_f32 v243, v141, v243
	v_cvt_pk_bf16_f32 v244, v142, v244
	v_cvt_pk_bf16_f32 v245, v143, v245
	global_store_dwordx4 v189, v[242:245], s[6:7]
	v_lshlrev_b32_e32 v140, 16, v246
	v_and_b32_e32 v246, 0xffff0000, v246
	v_lshlrev_b32_e32 v141, 16, v247
	v_and_b32_e32 v247, 0xffff0000, v247
	v_lshlrev_b32_e32 v142, 16, v248
	v_and_b32_e32 v248, 0xffff0000, v248
	v_lshlrev_b32_e32 v143, 16, v249
	v_and_b32_e32 v249, 0xffff0000, v249
	v_add_f32_e32 v140, v4, v140
	v_add_f32_e32 v246, v5, v246
	v_add_f32_e32 v141, v6, v141
	v_add_f32_e32 v247, v7, v247
	v_add_f32_e32 v142, v0, v142
	v_add_f32_e32 v248, v1, v248
	v_add_f32_e32 v143, v2, v143
	v_add_f32_e32 v249, v3, v249
	v_fmac_f32_e32 v12, v140, v140
	v_fmac_f32_e32 v12, v246, v246
	v_fmac_f32_e32 v12, v141, v141
	v_fmac_f32_e32 v12, v247, v247
	v_fmac_f32_e32 v12, v142, v142
	v_fmac_f32_e32 v12, v248, v248
	v_fmac_f32_e32 v12, v143, v143
	v_fmac_f32_e32 v12, v249, v249
	v_cvt_pk_bf16_f32 v246, v140, v246
	v_cvt_pk_bf16_f32 v247, v141, v247
	v_cvt_pk_bf16_f32 v248, v142, v248
	v_cvt_pk_bf16_f32 v249, v143, v249
	global_store_dwordx4 v189, v[246:249], s[6:7] offset:256
	v_and_b32_e32 v143, 64, v220
	v_xor_b32_e32 v140, 16, v220
	v_add_u32_e32 v143, 64, v143
	v_cmp_lt_i32_e32 vcc, v140, v143
	v_xor_b32_e32 v141, 32, v220
	s_nop 1
	v_cndmask_b32_e32 v140, v220, v140, vcc
	v_lshlrev_b32_e32 v140, 2, v140
	v_cmp_lt_i32_e32 vcc, v141, v143
	s_nop 1
	v_cndmask_b32_e32 v141, v220, v141, vcc
	v_lshlrev_b32_e32 v141, 2, v141
	ds_bpermute_b32 v127, v140, v126
	ds_bpermute_b32 v109, v140, v108
	ds_bpermute_b32 v93, v140, v92
	ds_bpermute_b32 v77, v140, v76
	ds_bpermute_b32 v61, v140, v60
	ds_bpermute_b32 v45, v140, v44
	ds_bpermute_b32 v29, v140, v28
	ds_bpermute_b32 v13, v140, v12
	v_lshl_add_u32 v212, s24, 8, v144
	v_ashrrev_i32_e32 v213, 31, v212
	v_lshlrev_b64 v[212:213], 6, v[212:213]
	v_lshl_add_u64 v[212:213], s[8:9], 0, v[212:213]
	v_lshl_add_u64 v[212:213], s[22:23], 2, v[212:213]
	s_lshl_b32 s92, s46, 2
	v_lshl_add_u64 v[212:213], v[212:213], 0, s[92:93]
	v_add_co_u32_e32 v188, vcc, 0x2000, v212
	s_nop 1
	v_addc_co_u32_e32 v189, vcc, 0, v213, vcc
	s_waitcnt lgkmcnt(0)
	v_add_f32_e32 v126, v126, v127
	v_add_f32_e32 v108, v108, v109
	v_add_f32_e32 v92, v92, v93
	v_add_f32_e32 v76, v76, v77
	v_add_f32_e32 v60, v60, v61
	v_add_f32_e32 v44, v44, v45
	v_add_f32_e32 v28, v28, v29
	v_add_f32_e32 v12, v12, v13
	ds_bpermute_b32 v127, v141, v126
	ds_bpermute_b32 v109, v141, v108
	ds_bpermute_b32 v93, v141, v92
	ds_bpermute_b32 v77, v141, v76
	ds_bpermute_b32 v61, v141, v60
	ds_bpermute_b32 v45, v141, v44
	ds_bpermute_b32 v29, v141, v28
	ds_bpermute_b32 v13, v141, v12
	s_waitcnt lgkmcnt(0)
	v_add_f32_e32 v126, v126, v127
	v_add_f32_e32 v108, v108, v109
	v_add_f32_e32 v92, v92, v93
	v_add_f32_e32 v76, v76, v77
	v_add_f32_e32 v60, v60, v61
	v_add_f32_e32 v44, v44, v45
	v_add_f32_e32 v28, v28, v29
	v_add_f32_e32 v12, v12, v13
	s_and_saveexec_b64 s[24:25], s[2:3]
	global_store_dword v[212:213], v126, off
	global_store_dword v[212:213], v108, off offset:1024
	global_store_dword v[212:213], v92, off offset:2048
	global_store_dword v[212:213], v76, off offset:3072
	global_store_dword v[188:189], v60, off
	global_store_dword v[188:189], v44, off offset:1024
	global_store_dword v[188:189], v28, off offset:2048
	global_store_dword v[188:189], v12, off offset:3072
	s_or_b64 exec, exec, s[24:25]
	s_andn2_b64 vcc, exec, s[4:5]
	s_mov_b64 s[4:5], -1
	s_cbranch_vccnz .LBB0_750
	s_andn2_b64 vcc, exec, s[10:11]
	s_cbranch_vccnz .LBB0_749
	s_barrier
	s_branch .LBB0_749

.LBB0_807:
	v_lshl_add_u32 v142, s49, 8, v144
	v_lshl_or_b32 v140, s20, 8, v146
	v_lshlrev_b32_e32 v141, 1, v140
	v_lshl_add_u32 v188, v142, 11, v141
	s_lshl_b32 s0, s20, 2
	s_ashr_i32 s1, s0, 31
	global_load_dwordx4 v[148:151], v188, s[6:7]
	global_load_dwordx4 v[152:155], v188, s[6:7] offset:256
	v_add_u32_e32 v189, 0x8000, v188
	global_load_dwordx4 v[156:159], v189, s[6:7]
	global_load_dwordx4 v[160:163], v189, s[6:7] offset:256
	v_add_u32_e32 v189, 0x10000, v188
	global_load_dwordx4 v[164:167], v189, s[6:7]
	global_load_dwordx4 v[168:171], v189, s[6:7] offset:256
	v_add_u32_e32 v189, 0x18000, v188
	global_load_dwordx4 v[172:175], v189, s[6:7]
	global_load_dwordx4 v[176:179], v189, s[6:7] offset:256
	v_add_u32_e32 v189, 0x40000, v188
	global_load_dwordx4 v[180:183], v189, s[6:7]
	global_load_dwordx4 v[184:187], v189, s[6:7] offset:256
	v_add_u32_e32 v189, 0x48000, v188
	global_load_dwordx4 v[208:211], v189, s[6:7]
	global_load_dwordx4 v[230:233], v189, s[6:7] offset:256
	v_add_u32_e32 v189, 0x50000, v188
	global_load_dwordx4 v[234:237], v189, s[6:7]
	global_load_dwordx4 v[238:241], v189, s[6:7] offset:256
	v_add_u32_e32 v189, 0x58000, v188
	global_load_dwordx4 v[242:245], v189, s[6:7]
	global_load_dwordx4 v[246:249], v189, s[6:7] offset:256
	s_waitcnt vmcnt(14)
	v_lshlrev_b32_e32 v140, 16, v148
	v_and_b32_e32 v148, 0xffff0000, v148
	v_lshlrev_b32_e32 v141, 16, v149
	v_and_b32_e32 v149, 0xffff0000, v149
	v_lshlrev_b32_e32 v142, 16, v150
	v_and_b32_e32 v150, 0xffff0000, v150
	v_lshlrev_b32_e32 v143, 16, v151
	v_and_b32_e32 v151, 0xffff0000, v151
	v_add_f32_e32 v140, v126, v140
	v_add_f32_e32 v148, v127, v148
	v_add_f32_e32 v141, v128, v141
	v_add_f32_e32 v149, v129, v149
	v_add_f32_e32 v142, v122, v142
	v_add_f32_e32 v150, v123, v150
	v_add_f32_e32 v143, v124, v143
	v_add_f32_e32 v151, v125, v151
	v_mul_f32_e32 v126, v140, v140
	v_fmac_f32_e32 v126, v148, v148
	v_fmac_f32_e32 v126, v141, v141
	v_fmac_f32_e32 v126, v149, v149
	v_fmac_f32_e32 v126, v142, v142
	v_fmac_f32_e32 v126, v150, v150
	v_fmac_f32_e32 v126, v143, v143
	v_fmac_f32_e32 v126, v151, v151
	v_cvt_pk_bf16_f32 v148, v140, v148
	v_cvt_pk_bf16_f32 v149, v141, v149
	v_cvt_pk_bf16_f32 v150, v142, v150
	v_cvt_pk_bf16_f32 v151, v143, v151
	global_store_dwordx4 v188, v[148:151], s[6:7]
	v_lshlrev_b32_e32 v140, 16, v152
	v_and_b32_e32 v152, 0xffff0000, v152
	v_lshlrev_b32_e32 v141, 16, v153
	v_and_b32_e32 v153, 0xffff0000, v153
	v_lshlrev_b32_e32 v142, 16, v154
	v_and_b32_e32 v154, 0xffff0000, v154
	v_lshlrev_b32_e32 v143, 16, v155
	v_and_b32_e32 v155, 0xffff0000, v155
	v_add_f32_e32 v140, v118, v140
	v_add_f32_e32 v152, v119, v152
	v_add_f32_e32 v141, v120, v141
	v_add_f32_e32 v153, v121, v153
	v_add_f32_e32 v142, v114, v142
	v_add_f32_e32 v154, v115, v154
	v_add_f32_e32 v143, v116, v143
	v_add_f32_e32 v155, v117, v155
	v_fmac_f32_e32 v126, v140, v140
	v_fmac_f32_e32 v126, v152, v152
	v_fmac_f32_e32 v126, v141, v141
	v_fmac_f32_e32 v126, v153, v153
	v_fmac_f32_e32 v126, v142, v142
	v_fmac_f32_e32 v126, v154, v154
	v_fmac_f32_e32 v126, v143, v143
	v_fmac_f32_e32 v126, v155, v155
	v_cvt_pk_bf16_f32 v152, v140, v152
	v_cvt_pk_bf16_f32 v153, v141, v153
	v_cvt_pk_bf16_f32 v154, v142, v154
	v_cvt_pk_bf16_f32 v155, v143, v155
	global_store_dwordx4 v188, v[152:155], s[6:7] offset:256
	s_waitcnt vmcnt(14)
	v_add_u32_e32 v189, 0x8000, v188
	v_lshlrev_b32_e32 v140, 16, v156
	v_and_b32_e32 v156, 0xffff0000, v156
	v_lshlrev_b32_e32 v141, 16, v157
	v_and_b32_e32 v157, 0xffff0000, v157
	v_lshlrev_b32_e32 v142, 16, v158
	v_and_b32_e32 v158, 0xffff0000, v158
	v_lshlrev_b32_e32 v143, 16, v159
	v_and_b32_e32 v159, 0xffff0000, v159
	v_add_f32_e32 v140, v108, v140
	v_add_f32_e32 v156, v109, v156
	v_add_f32_e32 v141, v110, v141
	v_add_f32_e32 v157, v111, v157
	v_add_f32_e32 v142, v104, v142
	v_add_f32_e32 v158, v105, v158
	v_add_f32_e32 v143, v106, v143
	v_add_f32_e32 v159, v107, v159
	v_mul_f32_e32 v108, v140, v140
	v_fmac_f32_e32 v108, v156, v156
	v_fmac_f32_e32 v108, v141, v141
	v_fmac_f32_e32 v108, v157, v157
	v_fmac_f32_e32 v108, v142, v142
	v_fmac_f32_e32 v108, v158, v158
	v_fmac_f32_e32 v108, v143, v143
	v_fmac_f32_e32 v108, v159, v159
	v_cvt_pk_bf16_f32 v156, v140, v156
	v_cvt_pk_bf16_f32 v157, v141, v157
	v_cvt_pk_bf16_f32 v158, v142, v158
	v_cvt_pk_bf16_f32 v159, v143, v159
	global_store_dwordx4 v189, v[156:159], s[6:7]
	v_lshlrev_b32_e32 v140, 16, v160
	v_and_b32_e32 v160, 0xffff0000, v160
	v_lshlrev_b32_e32 v141, 16, v161
	v_and_b32_e32 v161, 0xffff0000, v161
	v_lshlrev_b32_e32 v142, 16, v162
	v_and_b32_e32 v162, 0xffff0000, v162
	v_lshlrev_b32_e32 v143, 16, v163
	v_and_b32_e32 v163, 0xffff0000, v163
	v_add_f32_e32 v140, v100, v140
	v_add_f32_e32 v160, v101, v160
	v_add_f32_e32 v141, v102, v141
	v_add_f32_e32 v161, v103, v161
	v_add_f32_e32 v142, v96, v142
	v_add_f32_e32 v162, v97, v162
	v_add_f32_e32 v143, v98, v143
	v_add_f32_e32 v163, v99, v163
	v_fmac_f32_e32 v108, v140, v140
	v_fmac_f32_e32 v108, v160, v160
	v_fmac_f32_e32 v108, v141, v141
	v_fmac_f32_e32 v108, v161, v161
	v_fmac_f32_e32 v108, v142, v142
	v_fmac_f32_e32 v108, v162, v162
	v_fmac_f32_e32 v108, v143, v143
	v_fmac_f32_e32 v108, v163, v163
	v_cvt_pk_bf16_f32 v160, v140, v160
	v_cvt_pk_bf16_f32 v161, v141, v161
	v_cvt_pk_bf16_f32 v162, v142, v162
	v_cvt_pk_bf16_f32 v163, v143, v163
	global_store_dwordx4 v189, v[160:163], s[6:7] offset:256
	s_waitcnt vmcnt(14)
	v_add_u32_e32 v189, 0x10000, v188
	v_lshlrev_b32_e32 v140, 16, v164
	v_and_b32_e32 v164, 0xffff0000, v164
	v_lshlrev_b32_e32 v141, 16, v165
	v_and_b32_e32 v165, 0xffff0000, v165
	v_lshlrev_b32_e32 v142, 16, v166
	v_and_b32_e32 v166, 0xffff0000, v166
	v_lshlrev_b32_e32 v143, 16, v167
	v_and_b32_e32 v167, 0xffff0000, v167
	v_add_f32_e32 v140, v92, v140
	v_add_f32_e32 v164, v93, v164
	v_add_f32_e32 v141, v94, v141
	v_add_f32_e32 v165, v95, v165
	v_add_f32_e32 v142, v88, v142
	v_add_f32_e32 v166, v89, v166
	v_add_f32_e32 v143, v90, v143
	v_add_f32_e32 v167, v91, v167
	v_mul_f32_e32 v92, v140, v140
	v_fmac_f32_e32 v92, v164, v164
	v_fmac_f32_e32 v92, v141, v141
	v_fmac_f32_e32 v92, v165, v165
	v_fmac_f32_e32 v92, v142, v142
	v_fmac_f32_e32 v92, v166, v166
	v_fmac_f32_e32 v92, v143, v143
	v_fmac_f32_e32 v92, v167, v167
	v_cvt_pk_bf16_f32 v164, v140, v164
	v_cvt_pk_bf16_f32 v165, v141, v165
	v_cvt_pk_bf16_f32 v166, v142, v166
	v_cvt_pk_bf16_f32 v167, v143, v167
	global_store_dwordx4 v189, v[164:167], s[6:7]
	v_lshlrev_b32_e32 v140, 16, v168
	v_and_b32_e32 v168, 0xffff0000, v168
	v_lshlrev_b32_e32 v141, 16, v169
	v_and_b32_e32 v169, 0xffff0000, v169
	v_lshlrev_b32_e32 v142, 16, v170
	v_and_b32_e32 v170, 0xffff0000, v170
	v_lshlrev_b32_e32 v143, 16, v171
	v_and_b32_e32 v171, 0xffff0000, v171
	v_add_f32_e32 v140, v84, v140
	v_add_f32_e32 v168, v85, v168
	v_add_f32_e32 v141, v86, v141
	v_add_f32_e32 v169, v87, v169
	v_add_f32_e32 v142, v80, v142
	v_add_f32_e32 v170, v81, v170
	v_add_f32_e32 v143, v82, v143
	v_add_f32_e32 v171, v83, v171
	v_fmac_f32_e32 v92, v140, v140
	v_fmac_f32_e32 v92, v168, v168
	v_fmac_f32_e32 v92, v141, v141
	v_fmac_f32_e32 v92, v169, v169
	v_fmac_f32_e32 v92, v142, v142
	v_fmac_f32_e32 v92, v170, v170
	v_fmac_f32_e32 v92, v143, v143
	v_fmac_f32_e32 v92, v171, v171
	v_cvt_pk_bf16_f32 v168, v140, v168
	v_cvt_pk_bf16_f32 v169, v141, v169
	v_cvt_pk_bf16_f32 v170, v142, v170
	v_cvt_pk_bf16_f32 v171, v143, v171
	global_store_dwordx4 v189, v[168:171], s[6:7] offset:256
	s_waitcnt vmcnt(14)
	v_add_u32_e32 v189, 0x18000, v188
	v_lshlrev_b32_e32 v140, 16, v172
	v_and_b32_e32 v172, 0xffff0000, v172
	v_lshlrev_b32_e32 v141, 16, v173
	v_and_b32_e32 v173, 0xffff0000, v173
	v_lshlrev_b32_e32 v142, 16, v174
	v_and_b32_e32 v174, 0xffff0000, v174
	v_lshlrev_b32_e32 v143, 16, v175
	v_and_b32_e32 v175, 0xffff0000, v175
	v_add_f32_e32 v140, v76, v140
	v_add_f32_e32 v172, v77, v172
	v_add_f32_e32 v141, v78, v141
	v_add_f32_e32 v173, v79, v173
	v_add_f32_e32 v142, v72, v142
	v_add_f32_e32 v174, v73, v174
	v_add_f32_e32 v143, v74, v143
	v_add_f32_e32 v175, v75, v175
	v_mul_f32_e32 v76, v140, v140
	v_fmac_f32_e32 v76, v172, v172
	v_fmac_f32_e32 v76, v141, v141
	v_fmac_f32_e32 v76, v173, v173
	v_fmac_f32_e32 v76, v142, v142
	v_fmac_f32_e32 v76, v174, v174
	v_fmac_f32_e32 v76, v143, v143
	v_fmac_f32_e32 v76, v175, v175
	v_cvt_pk_bf16_f32 v172, v140, v172
	v_cvt_pk_bf16_f32 v173, v141, v173
	v_cvt_pk_bf16_f32 v174, v142, v174
	v_cvt_pk_bf16_f32 v175, v143, v175
	global_store_dwordx4 v189, v[172:175], s[6:7]
	v_lshlrev_b32_e32 v140, 16, v176
	v_and_b32_e32 v176, 0xffff0000, v176
	v_lshlrev_b32_e32 v141, 16, v177
	v_and_b32_e32 v177, 0xffff0000, v177
	v_lshlrev_b32_e32 v142, 16, v178
	v_and_b32_e32 v178, 0xffff0000, v178
	v_lshlrev_b32_e32 v143, 16, v179
	v_and_b32_e32 v179, 0xffff0000, v179
	v_add_f32_e32 v140, v68, v140
	v_add_f32_e32 v176, v69, v176
	v_add_f32_e32 v141, v70, v141
	v_add_f32_e32 v177, v71, v177
	v_add_f32_e32 v142, v64, v142
	v_add_f32_e32 v178, v65, v178
	v_add_f32_e32 v143, v66, v143
	v_add_f32_e32 v179, v67, v179
	v_fmac_f32_e32 v76, v140, v140
	v_fmac_f32_e32 v76, v176, v176
	v_fmac_f32_e32 v76, v141, v141
	v_fmac_f32_e32 v76, v177, v177
	v_fmac_f32_e32 v76, v142, v142
	v_fmac_f32_e32 v76, v178, v178
	v_fmac_f32_e32 v76, v143, v143
	v_fmac_f32_e32 v76, v179, v179
	v_cvt_pk_bf16_f32 v176, v140, v176
	v_cvt_pk_bf16_f32 v177, v141, v177
	v_cvt_pk_bf16_f32 v178, v142, v178
	v_cvt_pk_bf16_f32 v179, v143, v179
	global_store_dwordx4 v189, v[176:179], s[6:7] offset:256
	s_waitcnt vmcnt(14)
	v_add_u32_e32 v189, 0x40000, v188
	v_lshlrev_b32_e32 v140, 16, v180
	v_and_b32_e32 v180, 0xffff0000, v180
	v_lshlrev_b32_e32 v141, 16, v181
	v_and_b32_e32 v181, 0xffff0000, v181
	v_lshlrev_b32_e32 v142, 16, v182
	v_and_b32_e32 v182, 0xffff0000, v182
	v_lshlrev_b32_e32 v143, 16, v183
	v_and_b32_e32 v183, 0xffff0000, v183
	v_add_f32_e32 v140, v60, v140
	v_add_f32_e32 v180, v61, v180
	v_add_f32_e32 v141, v62, v141
	v_add_f32_e32 v181, v63, v181
	v_add_f32_e32 v142, v56, v142
	v_add_f32_e32 v182, v57, v182
	v_add_f32_e32 v143, v58, v143
	v_add_f32_e32 v183, v59, v183
	v_mul_f32_e32 v60, v140, v140
	v_fmac_f32_e32 v60, v180, v180
	v_fmac_f32_e32 v60, v141, v141
	v_fmac_f32_e32 v60, v181, v181
	v_fmac_f32_e32 v60, v142, v142
	v_fmac_f32_e32 v60, v182, v182
	v_fmac_f32_e32 v60, v143, v143
	v_fmac_f32_e32 v60, v183, v183
	v_cvt_pk_bf16_f32 v180, v140, v180
	v_cvt_pk_bf16_f32 v181, v141, v181
	v_cvt_pk_bf16_f32 v182, v142, v182
	v_cvt_pk_bf16_f32 v183, v143, v183
	global_store_dwordx4 v189, v[180:183], s[6:7]
	v_lshlrev_b32_e32 v140, 16, v184
	v_and_b32_e32 v184, 0xffff0000, v184
	v_lshlrev_b32_e32 v141, 16, v185
	v_and_b32_e32 v185, 0xffff0000, v185
	v_lshlrev_b32_e32 v142, 16, v186
	v_and_b32_e32 v186, 0xffff0000, v186
	v_lshlrev_b32_e32 v143, 16, v187
	v_and_b32_e32 v187, 0xffff0000, v187
	v_add_f32_e32 v140, v52, v140
	v_add_f32_e32 v184, v53, v184
	v_add_f32_e32 v141, v54, v141
	v_add_f32_e32 v185, v55, v185
	v_add_f32_e32 v142, v48, v142
	v_add_f32_e32 v186, v49, v186
	v_add_f32_e32 v143, v50, v143
	v_add_f32_e32 v187, v51, v187
	v_fmac_f32_e32 v60, v140, v140
	v_fmac_f32_e32 v60, v184, v184
	v_fmac_f32_e32 v60, v141, v141
	v_fmac_f32_e32 v60, v185, v185
	v_fmac_f32_e32 v60, v142, v142
	v_fmac_f32_e32 v60, v186, v186
	v_fmac_f32_e32 v60, v143, v143
	v_fmac_f32_e32 v60, v187, v187
	v_cvt_pk_bf16_f32 v184, v140, v184
	v_cvt_pk_bf16_f32 v185, v141, v185
	v_cvt_pk_bf16_f32 v186, v142, v186
	v_cvt_pk_bf16_f32 v187, v143, v187
	global_store_dwordx4 v189, v[184:187], s[6:7] offset:256
	s_waitcnt vmcnt(14)
	v_add_u32_e32 v189, 0x48000, v188
	v_lshlrev_b32_e32 v140, 16, v208
	v_and_b32_e32 v208, 0xffff0000, v208
	v_lshlrev_b32_e32 v141, 16, v209
	v_and_b32_e32 v209, 0xffff0000, v209
	v_lshlrev_b32_e32 v142, 16, v210
	v_and_b32_e32 v210, 0xffff0000, v210
	v_lshlrev_b32_e32 v143, 16, v211
	v_and_b32_e32 v211, 0xffff0000, v211
	v_add_f32_e32 v140, v44, v140
	v_add_f32_e32 v208, v45, v208
	v_add_f32_e32 v141, v46, v141
	v_add_f32_e32 v209, v47, v209
	v_add_f32_e32 v142, v40, v142
	v_add_f32_e32 v210, v41, v210
	v_add_f32_e32 v143, v42, v143
	v_add_f32_e32 v211, v43, v211
	v_mul_f32_e32 v44, v140, v140
	v_fmac_f32_e32 v44, v208, v208
	v_fmac_f32_e32 v44, v141, v141
	v_fmac_f32_e32 v44, v209, v209
	v_fmac_f32_e32 v44, v142, v142
	v_fmac_f32_e32 v44, v210, v210
	v_fmac_f32_e32 v44, v143, v143
	v_fmac_f32_e32 v44, v211, v211
	v_cvt_pk_bf16_f32 v208, v140, v208
	v_cvt_pk_bf16_f32 v209, v141, v209
	v_cvt_pk_bf16_f32 v210, v142, v210
	v_cvt_pk_bf16_f32 v211, v143, v211
	global_store_dwordx4 v189, v[208:211], s[6:7]
	v_lshlrev_b32_e32 v140, 16, v230
	v_and_b32_e32 v230, 0xffff0000, v230
	v_lshlrev_b32_e32 v141, 16, v231
	v_and_b32_e32 v231, 0xffff0000, v231
	v_lshlrev_b32_e32 v142, 16, v232
	v_and_b32_e32 v232, 0xffff0000, v232
	v_lshlrev_b32_e32 v143, 16, v233
	v_and_b32_e32 v233, 0xffff0000, v233
	v_add_f32_e32 v140, v36, v140
	v_add_f32_e32 v230, v37, v230
	v_add_f32_e32 v141, v38, v141
	v_add_f32_e32 v231, v39, v231
	v_add_f32_e32 v142, v32, v142
	v_add_f32_e32 v232, v33, v232
	v_add_f32_e32 v143, v34, v143
	v_add_f32_e32 v233, v35, v233
	v_fmac_f32_e32 v44, v140, v140
	v_fmac_f32_e32 v44, v230, v230
	v_fmac_f32_e32 v44, v141, v141
	v_fmac_f32_e32 v44, v231, v231
	v_fmac_f32_e32 v44, v142, v142
	v_fmac_f32_e32 v44, v232, v232
	v_fmac_f32_e32 v44, v143, v143
	v_fmac_f32_e32 v44, v233, v233
	v_cvt_pk_bf16_f32 v230, v140, v230
	v_cvt_pk_bf16_f32 v231, v141, v231
	v_cvt_pk_bf16_f32 v232, v142, v232
	v_cvt_pk_bf16_f32 v233, v143, v233
	global_store_dwordx4 v189, v[230:233], s[6:7] offset:256
	s_waitcnt vmcnt(14)
	v_add_u32_e32 v189, 0x50000, v188
	v_lshlrev_b32_e32 v140, 16, v234
	v_and_b32_e32 v234, 0xffff0000, v234
	v_lshlrev_b32_e32 v141, 16, v235
	v_and_b32_e32 v235, 0xffff0000, v235
	v_lshlrev_b32_e32 v142, 16, v236
	v_and_b32_e32 v236, 0xffff0000, v236
	v_lshlrev_b32_e32 v143, 16, v237
	v_and_b32_e32 v237, 0xffff0000, v237
	v_add_f32_e32 v140, v28, v140
	v_add_f32_e32 v234, v29, v234
	v_add_f32_e32 v141, v30, v141
	v_add_f32_e32 v235, v31, v235
	v_add_f32_e32 v142, v24, v142
	v_add_f32_e32 v236, v25, v236
	v_add_f32_e32 v143, v26, v143
	v_add_f32_e32 v237, v27, v237
	v_mul_f32_e32 v28, v140, v140
	v_fmac_f32_e32 v28, v234, v234
	v_fmac_f32_e32 v28, v141, v141
	v_fmac_f32_e32 v28, v235, v235
	v_fmac_f32_e32 v28, v142, v142
	v_fmac_f32_e32 v28, v236, v236
	v_fmac_f32_e32 v28, v143, v143
	v_fmac_f32_e32 v28, v237, v237
	v_cvt_pk_bf16_f32 v234, v140, v234
	v_cvt_pk_bf16_f32 v235, v141, v235
	v_cvt_pk_bf16_f32 v236, v142, v236
	v_cvt_pk_bf16_f32 v237, v143, v237
	global_store_dwordx4 v189, v[234:237], s[6:7]
	v_lshlrev_b32_e32 v140, 16, v238
	v_and_b32_e32 v238, 0xffff0000, v238
	v_lshlrev_b32_e32 v141, 16, v239
	v_and_b32_e32 v239, 0xffff0000, v239
	v_lshlrev_b32_e32 v142, 16, v240
	v_and_b32_e32 v240, 0xffff0000, v240
	v_lshlrev_b32_e32 v143, 16, v241
	v_and_b32_e32 v241, 0xffff0000, v241
	v_add_f32_e32 v140, v20, v140
	v_add_f32_e32 v238, v21, v238
	v_add_f32_e32 v141, v22, v141
	v_add_f32_e32 v239, v23, v239
	v_add_f32_e32 v142, v16, v142
	v_add_f32_e32 v240, v17, v240
	v_add_f32_e32 v143, v18, v143
	v_add_f32_e32 v241, v19, v241
	v_fmac_f32_e32 v28, v140, v140
	v_fmac_f32_e32 v28, v238, v238
	v_fmac_f32_e32 v28, v141, v141
	v_fmac_f32_e32 v28, v239, v239
	v_fmac_f32_e32 v28, v142, v142
	v_fmac_f32_e32 v28, v240, v240
	v_fmac_f32_e32 v28, v143, v143
	v_fmac_f32_e32 v28, v241, v241
	v_cvt_pk_bf16_f32 v238, v140, v238
	v_cvt_pk_bf16_f32 v239, v141, v239
	v_cvt_pk_bf16_f32 v240, v142, v240
	v_cvt_pk_bf16_f32 v241, v143, v241
	global_store_dwordx4 v189, v[238:241], s[6:7] offset:256
	s_waitcnt vmcnt(14)
	v_add_u32_e32 v189, 0x58000, v188
	v_lshlrev_b32_e32 v140, 16, v242
	v_and_b32_e32 v242, 0xffff0000, v242
	v_lshlrev_b32_e32 v141, 16, v243
	v_and_b32_e32 v243, 0xffff0000, v243
	v_lshlrev_b32_e32 v142, 16, v244
	v_and_b32_e32 v244, 0xffff0000, v244
	v_lshlrev_b32_e32 v143, 16, v245
	v_and_b32_e32 v245, 0xffff0000, v245
	v_add_f32_e32 v140, v12, v140
	v_add_f32_e32 v242, v13, v242
	v_add_f32_e32 v141, v14, v141
	v_add_f32_e32 v243, v15, v243
	v_add_f32_e32 v142, v8, v142
	v_add_f32_e32 v244, v9, v244
	v_add_f32_e32 v143, v10, v143
	v_add_f32_e32 v245, v11, v245
	v_mul_f32_e32 v12, v140, v140
	v_fmac_f32_e32 v12, v242, v242
	v_fmac_f32_e32 v12, v141, v141
	v_fmac_f32_e32 v12, v243, v243
	v_fmac_f32_e32 v12, v142, v142
	v_fmac_f32_e32 v12, v244, v244
	v_fmac_f32_e32 v12, v143, v143
	v_fmac_f32_e32 v12, v245, v245
	v_cvt_pk_bf16_f32 v242, v140, v242
	v_cvt_pk_bf16_f32 v243, v141, v243
	v_cvt_pk_bf16_f32 v244, v142, v244
	v_cvt_pk_bf16_f32 v245, v143, v245
	global_store_dwordx4 v189, v[242:245], s[6:7]
	v_lshlrev_b32_e32 v140, 16, v246
	v_and_b32_e32 v246, 0xffff0000, v246
	v_lshlrev_b32_e32 v141, 16, v247
	v_and_b32_e32 v247, 0xffff0000, v247
	v_lshlrev_b32_e32 v142, 16, v248
	v_and_b32_e32 v248, 0xffff0000, v248
	v_lshlrev_b32_e32 v143, 16, v249
	v_and_b32_e32 v249, 0xffff0000, v249
	v_add_f32_e32 v140, v4, v140
	v_add_f32_e32 v246, v5, v246
	v_add_f32_e32 v141, v6, v141
	v_add_f32_e32 v247, v7, v247
	v_add_f32_e32 v142, v0, v142
	v_add_f32_e32 v248, v1, v248
	v_add_f32_e32 v143, v2, v143
	v_add_f32_e32 v249, v3, v249
	v_fmac_f32_e32 v12, v140, v140
	v_fmac_f32_e32 v12, v246, v246
	v_fmac_f32_e32 v12, v141, v141
	v_fmac_f32_e32 v12, v247, v247
	v_fmac_f32_e32 v12, v142, v142
	v_fmac_f32_e32 v12, v248, v248
	v_fmac_f32_e32 v12, v143, v143
	v_fmac_f32_e32 v12, v249, v249
	v_cvt_pk_bf16_f32 v246, v140, v246
	v_cvt_pk_bf16_f32 v247, v141, v247
	v_cvt_pk_bf16_f32 v248, v142, v248
	v_cvt_pk_bf16_f32 v249, v143, v249
	global_store_dwordx4 v189, v[246:249], s[6:7] offset:256
	v_and_b32_e32 v143, 64, v220
	v_xor_b32_e32 v140, 16, v220
	v_add_u32_e32 v143, 64, v143
	v_cmp_lt_i32_e32 vcc, v140, v143
	v_xor_b32_e32 v141, 32, v220
	s_nop 1
	v_cndmask_b32_e32 v140, v220, v140, vcc
	v_lshlrev_b32_e32 v140, 2, v140
	v_cmp_lt_i32_e32 vcc, v141, v143
	s_nop 1
	v_cndmask_b32_e32 v141, v220, v141, vcc
	v_lshlrev_b32_e32 v141, 2, v141
	ds_bpermute_b32 v127, v140, v126
	ds_bpermute_b32 v109, v140, v108
	ds_bpermute_b32 v93, v140, v92
	ds_bpermute_b32 v77, v140, v76
	ds_bpermute_b32 v61, v140, v60
	ds_bpermute_b32 v45, v140, v44
	ds_bpermute_b32 v29, v140, v28
	ds_bpermute_b32 v13, v140, v12
	v_lshl_add_u32 v212, s49, 8, v144
	v_ashrrev_i32_e32 v213, 31, v212
	v_lshlrev_b64 v[212:213], 6, v[212:213]
	v_lshl_add_u64 v[212:213], s[8:9], 0, v[212:213]
	v_lshl_add_u64 v[212:213], s[0:1], 2, v[212:213]
	s_lshl_b32 s92, s42, 2
	v_lshl_add_u64 v[212:213], v[212:213], 0, s[92:93]
	v_add_co_u32_e32 v188, vcc, 0x2000, v212
	s_nop 1
	v_addc_co_u32_e32 v189, vcc, 0, v213, vcc
	s_waitcnt lgkmcnt(0)
	v_add_f32_e32 v126, v126, v127
	v_add_f32_e32 v108, v108, v109
	v_add_f32_e32 v92, v92, v93
	v_add_f32_e32 v76, v76, v77
	v_add_f32_e32 v60, v60, v61
	v_add_f32_e32 v44, v44, v45
	v_add_f32_e32 v28, v28, v29
	v_add_f32_e32 v12, v12, v13
	ds_bpermute_b32 v127, v141, v126
	ds_bpermute_b32 v109, v141, v108
	ds_bpermute_b32 v93, v141, v92
	ds_bpermute_b32 v77, v141, v76
	ds_bpermute_b32 v61, v141, v60
	ds_bpermute_b32 v45, v141, v44
	ds_bpermute_b32 v29, v141, v28
	ds_bpermute_b32 v13, v141, v12
	s_waitcnt lgkmcnt(0)
	v_add_f32_e32 v126, v126, v127
	v_add_f32_e32 v108, v108, v109
	v_add_f32_e32 v92, v92, v93
	v_add_f32_e32 v76, v76, v77
	v_add_f32_e32 v60, v60, v61
	v_add_f32_e32 v44, v44, v45
	v_add_f32_e32 v28, v28, v29
	v_add_f32_e32 v12, v12, v13
	s_and_saveexec_b64 s[20:21], s[2:3]
	global_store_dword v[212:213], v126, off
	global_store_dword v[212:213], v108, off offset:1024
	global_store_dword v[212:213], v92, off offset:2048
	global_store_dword v[212:213], v76, off offset:3072
	global_store_dword v[188:189], v60, off
	global_store_dword v[188:189], v44, off offset:1024
	global_store_dword v[188:189], v28, off offset:2048
	global_store_dword v[188:189], v12, off offset:3072
	s_or_b64 exec, exec, s[20:21]
	s_and_b64 vcc, exec, s[4:5]
	s_mov_b64 s[0:1], -1
	s_cbranch_vccnz .LBB0_794
	s_andn2_b64 vcc, exec, s[10:11]
	s_cbranch_vccnz .LBB0_793
	s_barrier
	s_branch .LBB0_793

.LBB0_1140:
	v_lshl_add_u32 v142, s47, 8, v144
	v_lshl_or_b32 v140, s46, 8, v146
	v_lshlrev_b32_e32 v141, 1, v140
	v_lshl_add_u32 v188, v142, 11, v141
	s_lshl_b32 s16, s46, 2
	s_ashr_i32 s17, s16, 31
	global_load_dwordx4 v[148:151], v188, s[8:9]
	global_load_dwordx4 v[152:155], v188, s[8:9] offset:256
	v_add_u32_e32 v189, 0x8000, v188
	global_load_dwordx4 v[156:159], v189, s[8:9]
	global_load_dwordx4 v[160:163], v189, s[8:9] offset:256
	v_add_u32_e32 v189, 0x10000, v188
	global_load_dwordx4 v[164:167], v189, s[8:9]
	global_load_dwordx4 v[168:171], v189, s[8:9] offset:256
	v_add_u32_e32 v189, 0x18000, v188
	global_load_dwordx4 v[172:175], v189, s[8:9]
	global_load_dwordx4 v[176:179], v189, s[8:9] offset:256
	v_add_u32_e32 v189, 0x40000, v188
	global_load_dwordx4 v[180:183], v189, s[8:9]
	global_load_dwordx4 v[184:187], v189, s[8:9] offset:256
	v_add_u32_e32 v189, 0x48000, v188
	global_load_dwordx4 v[208:211], v189, s[8:9]
	global_load_dwordx4 v[230:233], v189, s[8:9] offset:256
	v_add_u32_e32 v189, 0x50000, v188
	global_load_dwordx4 v[234:237], v189, s[8:9]
	global_load_dwordx4 v[238:241], v189, s[8:9] offset:256
	v_add_u32_e32 v189, 0x58000, v188
	global_load_dwordx4 v[242:245], v189, s[8:9]
	global_load_dwordx4 v[246:249], v189, s[8:9] offset:256
	s_waitcnt vmcnt(14)
	v_lshlrev_b32_e32 v140, 16, v148
	v_and_b32_e32 v148, 0xffff0000, v148
	v_lshlrev_b32_e32 v141, 16, v149
	v_and_b32_e32 v149, 0xffff0000, v149
	v_lshlrev_b32_e32 v142, 16, v150
	v_and_b32_e32 v150, 0xffff0000, v150
	v_lshlrev_b32_e32 v143, 16, v151
	v_and_b32_e32 v151, 0xffff0000, v151
	v_fmac_f32_e32 v140, 0.5, v126
	v_fmac_f32_e32 v148, 0.5, v127
	v_fmac_f32_e32 v141, 0.5, v128
	v_fmac_f32_e32 v149, 0.5, v129
	v_fmac_f32_e32 v142, 0.5, v122
	v_fmac_f32_e32 v150, 0.5, v123
	v_fmac_f32_e32 v143, 0.5, v124
	v_fmac_f32_e32 v151, 0.5, v125
	v_mul_f32_e32 v126, v140, v140
	v_fmac_f32_e32 v126, v148, v148
	v_fmac_f32_e32 v126, v141, v141
	v_fmac_f32_e32 v126, v149, v149
	v_fmac_f32_e32 v126, v142, v142
	v_fmac_f32_e32 v126, v150, v150
	v_fmac_f32_e32 v126, v143, v143
	v_fmac_f32_e32 v126, v151, v151
	v_cvt_pk_bf16_f32 v148, v140, v148
	v_cvt_pk_bf16_f32 v149, v141, v149
	v_cvt_pk_bf16_f32 v150, v142, v150
	v_cvt_pk_bf16_f32 v151, v143, v151
	global_store_dwordx4 v188, v[148:151], s[8:9]
	v_lshlrev_b32_e32 v140, 16, v152
	v_and_b32_e32 v152, 0xffff0000, v152
	v_lshlrev_b32_e32 v141, 16, v153
	v_and_b32_e32 v153, 0xffff0000, v153
	v_lshlrev_b32_e32 v142, 16, v154
	v_and_b32_e32 v154, 0xffff0000, v154
	v_lshlrev_b32_e32 v143, 16, v155
	v_and_b32_e32 v155, 0xffff0000, v155
	v_fmac_f32_e32 v140, 0.5, v118
	v_fmac_f32_e32 v152, 0.5, v119
	v_fmac_f32_e32 v141, 0.5, v120
	v_fmac_f32_e32 v153, 0.5, v121
	v_fmac_f32_e32 v142, 0.5, v114
	v_fmac_f32_e32 v154, 0.5, v115
	v_fmac_f32_e32 v143, 0.5, v116
	v_fmac_f32_e32 v155, 0.5, v117
	v_fmac_f32_e32 v126, v140, v140
	v_fmac_f32_e32 v126, v152, v152
	v_fmac_f32_e32 v126, v141, v141
	v_fmac_f32_e32 v126, v153, v153
	v_fmac_f32_e32 v126, v142, v142
	v_fmac_f32_e32 v126, v154, v154
	v_fmac_f32_e32 v126, v143, v143
	v_fmac_f32_e32 v126, v155, v155
	v_cvt_pk_bf16_f32 v152, v140, v152
	v_cvt_pk_bf16_f32 v153, v141, v153
	v_cvt_pk_bf16_f32 v154, v142, v154
	v_cvt_pk_bf16_f32 v155, v143, v155
	global_store_dwordx4 v188, v[152:155], s[8:9] offset:256
	s_waitcnt vmcnt(14)
	v_add_u32_e32 v189, 0x8000, v188
	v_lshlrev_b32_e32 v140, 16, v156
	v_and_b32_e32 v156, 0xffff0000, v156
	v_lshlrev_b32_e32 v141, 16, v157
	v_and_b32_e32 v157, 0xffff0000, v157
	v_lshlrev_b32_e32 v142, 16, v158
	v_and_b32_e32 v158, 0xffff0000, v158
	v_lshlrev_b32_e32 v143, 16, v159
	v_and_b32_e32 v159, 0xffff0000, v159
	v_fmac_f32_e32 v140, 0.5, v108
	v_fmac_f32_e32 v156, 0.5, v109
	v_fmac_f32_e32 v141, 0.5, v110
	v_fmac_f32_e32 v157, 0.5, v111
	v_fmac_f32_e32 v142, 0.5, v104
	v_fmac_f32_e32 v158, 0.5, v105
	v_fmac_f32_e32 v143, 0.5, v106
	v_fmac_f32_e32 v159, 0.5, v107
	v_mul_f32_e32 v108, v140, v140
	v_fmac_f32_e32 v108, v156, v156
	v_fmac_f32_e32 v108, v141, v141
	v_fmac_f32_e32 v108, v157, v157
	v_fmac_f32_e32 v108, v142, v142
	v_fmac_f32_e32 v108, v158, v158
	v_fmac_f32_e32 v108, v143, v143
	v_fmac_f32_e32 v108, v159, v159
	v_cvt_pk_bf16_f32 v156, v140, v156
	v_cvt_pk_bf16_f32 v157, v141, v157
	v_cvt_pk_bf16_f32 v158, v142, v158
	v_cvt_pk_bf16_f32 v159, v143, v159
	global_store_dwordx4 v189, v[156:159], s[8:9]
	v_lshlrev_b32_e32 v140, 16, v160
	v_and_b32_e32 v160, 0xffff0000, v160
	v_lshlrev_b32_e32 v141, 16, v161
	v_and_b32_e32 v161, 0xffff0000, v161
	v_lshlrev_b32_e32 v142, 16, v162
	v_and_b32_e32 v162, 0xffff0000, v162
	v_lshlrev_b32_e32 v143, 16, v163
	v_and_b32_e32 v163, 0xffff0000, v163
	v_fmac_f32_e32 v140, 0.5, v100
	v_fmac_f32_e32 v160, 0.5, v101
	v_fmac_f32_e32 v141, 0.5, v102
	v_fmac_f32_e32 v161, 0.5, v103
	v_fmac_f32_e32 v142, 0.5, v96
	v_fmac_f32_e32 v162, 0.5, v97
	v_fmac_f32_e32 v143, 0.5, v98
	v_fmac_f32_e32 v163, 0.5, v99
	v_fmac_f32_e32 v108, v140, v140
	v_fmac_f32_e32 v108, v160, v160
	v_fmac_f32_e32 v108, v141, v141
	v_fmac_f32_e32 v108, v161, v161
	v_fmac_f32_e32 v108, v142, v142
	v_fmac_f32_e32 v108, v162, v162
	v_fmac_f32_e32 v108, v143, v143
	v_fmac_f32_e32 v108, v163, v163
	v_cvt_pk_bf16_f32 v160, v140, v160
	v_cvt_pk_bf16_f32 v161, v141, v161
	v_cvt_pk_bf16_f32 v162, v142, v162
	v_cvt_pk_bf16_f32 v163, v143, v163
	global_store_dwordx4 v189, v[160:163], s[8:9] offset:256
	s_waitcnt vmcnt(14)
	v_add_u32_e32 v189, 0x10000, v188
	v_lshlrev_b32_e32 v140, 16, v164
	v_and_b32_e32 v164, 0xffff0000, v164
	v_lshlrev_b32_e32 v141, 16, v165
	v_and_b32_e32 v165, 0xffff0000, v165
	v_lshlrev_b32_e32 v142, 16, v166
	v_and_b32_e32 v166, 0xffff0000, v166
	v_lshlrev_b32_e32 v143, 16, v167
	v_and_b32_e32 v167, 0xffff0000, v167
	v_fmac_f32_e32 v140, 0.5, v92
	v_fmac_f32_e32 v164, 0.5, v93
	v_fmac_f32_e32 v141, 0.5, v94
	v_fmac_f32_e32 v165, 0.5, v95
	v_fmac_f32_e32 v142, 0.5, v88
	v_fmac_f32_e32 v166, 0.5, v89
	v_fmac_f32_e32 v143, 0.5, v90
	v_fmac_f32_e32 v167, 0.5, v91
	v_mul_f32_e32 v92, v140, v140
	v_fmac_f32_e32 v92, v164, v164
	v_fmac_f32_e32 v92, v141, v141
	v_fmac_f32_e32 v92, v165, v165
	v_fmac_f32_e32 v92, v142, v142
	v_fmac_f32_e32 v92, v166, v166
	v_fmac_f32_e32 v92, v143, v143
	v_fmac_f32_e32 v92, v167, v167
	v_cvt_pk_bf16_f32 v164, v140, v164
	v_cvt_pk_bf16_f32 v165, v141, v165
	v_cvt_pk_bf16_f32 v166, v142, v166
	v_cvt_pk_bf16_f32 v167, v143, v167
	global_store_dwordx4 v189, v[164:167], s[8:9]
	v_lshlrev_b32_e32 v140, 16, v168
	v_and_b32_e32 v168, 0xffff0000, v168
	v_lshlrev_b32_e32 v141, 16, v169
	v_and_b32_e32 v169, 0xffff0000, v169
	v_lshlrev_b32_e32 v142, 16, v170
	v_and_b32_e32 v170, 0xffff0000, v170
	v_lshlrev_b32_e32 v143, 16, v171
	v_and_b32_e32 v171, 0xffff0000, v171
	v_fmac_f32_e32 v140, 0.5, v84
	v_fmac_f32_e32 v168, 0.5, v85
	v_fmac_f32_e32 v141, 0.5, v86
	v_fmac_f32_e32 v169, 0.5, v87
	v_fmac_f32_e32 v142, 0.5, v80
	v_fmac_f32_e32 v170, 0.5, v81
	v_fmac_f32_e32 v143, 0.5, v82
	v_fmac_f32_e32 v171, 0.5, v83
	v_fmac_f32_e32 v92, v140, v140
	v_fmac_f32_e32 v92, v168, v168
	v_fmac_f32_e32 v92, v141, v141
	v_fmac_f32_e32 v92, v169, v169
	v_fmac_f32_e32 v92, v142, v142
	v_fmac_f32_e32 v92, v170, v170
	v_fmac_f32_e32 v92, v143, v143
	v_fmac_f32_e32 v92, v171, v171
	v_cvt_pk_bf16_f32 v168, v140, v168
	v_cvt_pk_bf16_f32 v169, v141, v169
	v_cvt_pk_bf16_f32 v170, v142, v170
	v_cvt_pk_bf16_f32 v171, v143, v171
	global_store_dwordx4 v189, v[168:171], s[8:9] offset:256
	s_waitcnt vmcnt(14)
	v_add_u32_e32 v189, 0x18000, v188
	v_lshlrev_b32_e32 v140, 16, v172
	v_and_b32_e32 v172, 0xffff0000, v172
	v_lshlrev_b32_e32 v141, 16, v173
	v_and_b32_e32 v173, 0xffff0000, v173
	v_lshlrev_b32_e32 v142, 16, v174
	v_and_b32_e32 v174, 0xffff0000, v174
	v_lshlrev_b32_e32 v143, 16, v175
	v_and_b32_e32 v175, 0xffff0000, v175
	v_fmac_f32_e32 v140, 0.5, v76
	v_fmac_f32_e32 v172, 0.5, v77
	v_fmac_f32_e32 v141, 0.5, v78
	v_fmac_f32_e32 v173, 0.5, v79
	v_fmac_f32_e32 v142, 0.5, v72
	v_fmac_f32_e32 v174, 0.5, v73
	v_fmac_f32_e32 v143, 0.5, v74
	v_fmac_f32_e32 v175, 0.5, v75
	v_mul_f32_e32 v76, v140, v140
	v_fmac_f32_e32 v76, v172, v172
	v_fmac_f32_e32 v76, v141, v141
	v_fmac_f32_e32 v76, v173, v173
	v_fmac_f32_e32 v76, v142, v142
	v_fmac_f32_e32 v76, v174, v174
	v_fmac_f32_e32 v76, v143, v143
	v_fmac_f32_e32 v76, v175, v175
	v_cvt_pk_bf16_f32 v172, v140, v172
	v_cvt_pk_bf16_f32 v173, v141, v173
	v_cvt_pk_bf16_f32 v174, v142, v174
	v_cvt_pk_bf16_f32 v175, v143, v175
	global_store_dwordx4 v189, v[172:175], s[8:9]
	v_lshlrev_b32_e32 v140, 16, v176
	v_and_b32_e32 v176, 0xffff0000, v176
	v_lshlrev_b32_e32 v141, 16, v177
	v_and_b32_e32 v177, 0xffff0000, v177
	v_lshlrev_b32_e32 v142, 16, v178
	v_and_b32_e32 v178, 0xffff0000, v178
	v_lshlrev_b32_e32 v143, 16, v179
	v_and_b32_e32 v179, 0xffff0000, v179
	v_fmac_f32_e32 v140, 0.5, v68
	v_fmac_f32_e32 v176, 0.5, v69
	v_fmac_f32_e32 v141, 0.5, v70
	v_fmac_f32_e32 v177, 0.5, v71
	v_fmac_f32_e32 v142, 0.5, v64
	v_fmac_f32_e32 v178, 0.5, v65
	v_fmac_f32_e32 v143, 0.5, v66
	v_fmac_f32_e32 v179, 0.5, v67
	v_fmac_f32_e32 v76, v140, v140
	v_fmac_f32_e32 v76, v176, v176
	v_fmac_f32_e32 v76, v141, v141
	v_fmac_f32_e32 v76, v177, v177
	v_fmac_f32_e32 v76, v142, v142
	v_fmac_f32_e32 v76, v178, v178
	v_fmac_f32_e32 v76, v143, v143
	v_fmac_f32_e32 v76, v179, v179
	v_cvt_pk_bf16_f32 v176, v140, v176
	v_cvt_pk_bf16_f32 v177, v141, v177
	v_cvt_pk_bf16_f32 v178, v142, v178
	v_cvt_pk_bf16_f32 v179, v143, v179
	global_store_dwordx4 v189, v[176:179], s[8:9] offset:256
	s_waitcnt vmcnt(14)
	v_add_u32_e32 v189, 0x40000, v188
	v_lshlrev_b32_e32 v140, 16, v180
	v_and_b32_e32 v180, 0xffff0000, v180
	v_lshlrev_b32_e32 v141, 16, v181
	v_and_b32_e32 v181, 0xffff0000, v181
	v_lshlrev_b32_e32 v142, 16, v182
	v_and_b32_e32 v182, 0xffff0000, v182
	v_lshlrev_b32_e32 v143, 16, v183
	v_and_b32_e32 v183, 0xffff0000, v183
	v_fmac_f32_e32 v140, 0.5, v60
	v_fmac_f32_e32 v180, 0.5, v61
	v_fmac_f32_e32 v141, 0.5, v62
	v_fmac_f32_e32 v181, 0.5, v63
	v_fmac_f32_e32 v142, 0.5, v56
	v_fmac_f32_e32 v182, 0.5, v57
	v_fmac_f32_e32 v143, 0.5, v58
	v_fmac_f32_e32 v183, 0.5, v59
	v_mul_f32_e32 v60, v140, v140
	v_fmac_f32_e32 v60, v180, v180
	v_fmac_f32_e32 v60, v141, v141
	v_fmac_f32_e32 v60, v181, v181
	v_fmac_f32_e32 v60, v142, v142
	v_fmac_f32_e32 v60, v182, v182
	v_fmac_f32_e32 v60, v143, v143
	v_fmac_f32_e32 v60, v183, v183
	v_cvt_pk_bf16_f32 v180, v140, v180
	v_cvt_pk_bf16_f32 v181, v141, v181
	v_cvt_pk_bf16_f32 v182, v142, v182
	v_cvt_pk_bf16_f32 v183, v143, v183
	global_store_dwordx4 v189, v[180:183], s[8:9]
	v_lshlrev_b32_e32 v140, 16, v184
	v_and_b32_e32 v184, 0xffff0000, v184
	v_lshlrev_b32_e32 v141, 16, v185
	v_and_b32_e32 v185, 0xffff0000, v185
	v_lshlrev_b32_e32 v142, 16, v186
	v_and_b32_e32 v186, 0xffff0000, v186
	v_lshlrev_b32_e32 v143, 16, v187
	v_and_b32_e32 v187, 0xffff0000, v187
	v_fmac_f32_e32 v140, 0.5, v52
	v_fmac_f32_e32 v184, 0.5, v53
	v_fmac_f32_e32 v141, 0.5, v54
	v_fmac_f32_e32 v185, 0.5, v55
	v_fmac_f32_e32 v142, 0.5, v48
	v_fmac_f32_e32 v186, 0.5, v49
	v_fmac_f32_e32 v143, 0.5, v50
	v_fmac_f32_e32 v187, 0.5, v51
	v_fmac_f32_e32 v60, v140, v140
	v_fmac_f32_e32 v60, v184, v184
	v_fmac_f32_e32 v60, v141, v141
	v_fmac_f32_e32 v60, v185, v185
	v_fmac_f32_e32 v60, v142, v142
	v_fmac_f32_e32 v60, v186, v186
	v_fmac_f32_e32 v60, v143, v143
	v_fmac_f32_e32 v60, v187, v187
	v_cvt_pk_bf16_f32 v184, v140, v184
	v_cvt_pk_bf16_f32 v185, v141, v185
	v_cvt_pk_bf16_f32 v186, v142, v186
	v_cvt_pk_bf16_f32 v187, v143, v187
	global_store_dwordx4 v189, v[184:187], s[8:9] offset:256
	s_waitcnt vmcnt(14)
	v_add_u32_e32 v189, 0x48000, v188
	v_lshlrev_b32_e32 v140, 16, v208
	v_and_b32_e32 v208, 0xffff0000, v208
	v_lshlrev_b32_e32 v141, 16, v209
	v_and_b32_e32 v209, 0xffff0000, v209
	v_lshlrev_b32_e32 v142, 16, v210
	v_and_b32_e32 v210, 0xffff0000, v210
	v_lshlrev_b32_e32 v143, 16, v211
	v_and_b32_e32 v211, 0xffff0000, v211
	v_fmac_f32_e32 v140, 0.5, v44
	v_fmac_f32_e32 v208, 0.5, v45
	v_fmac_f32_e32 v141, 0.5, v46
	v_fmac_f32_e32 v209, 0.5, v47
	v_fmac_f32_e32 v142, 0.5, v40
	v_fmac_f32_e32 v210, 0.5, v41
	v_fmac_f32_e32 v143, 0.5, v42
	v_fmac_f32_e32 v211, 0.5, v43
	v_mul_f32_e32 v44, v140, v140
	v_fmac_f32_e32 v44, v208, v208
	v_fmac_f32_e32 v44, v141, v141
	v_fmac_f32_e32 v44, v209, v209
	v_fmac_f32_e32 v44, v142, v142
	v_fmac_f32_e32 v44, v210, v210
	v_fmac_f32_e32 v44, v143, v143
	v_fmac_f32_e32 v44, v211, v211
	v_cvt_pk_bf16_f32 v208, v140, v208
	v_cvt_pk_bf16_f32 v209, v141, v209
	v_cvt_pk_bf16_f32 v210, v142, v210
	v_cvt_pk_bf16_f32 v211, v143, v211
	global_store_dwordx4 v189, v[208:211], s[8:9]
	v_lshlrev_b32_e32 v140, 16, v230
	v_and_b32_e32 v230, 0xffff0000, v230
	v_lshlrev_b32_e32 v141, 16, v231
	v_and_b32_e32 v231, 0xffff0000, v231
	v_lshlrev_b32_e32 v142, 16, v232
	v_and_b32_e32 v232, 0xffff0000, v232
	v_lshlrev_b32_e32 v143, 16, v233
	v_and_b32_e32 v233, 0xffff0000, v233
	v_fmac_f32_e32 v140, 0.5, v36
	v_fmac_f32_e32 v230, 0.5, v37
	v_fmac_f32_e32 v141, 0.5, v38
	v_fmac_f32_e32 v231, 0.5, v39
	v_fmac_f32_e32 v142, 0.5, v32
	v_fmac_f32_e32 v232, 0.5, v33
	v_fmac_f32_e32 v143, 0.5, v34
	v_fmac_f32_e32 v233, 0.5, v35
	v_fmac_f32_e32 v44, v140, v140
	v_fmac_f32_e32 v44, v230, v230
	v_fmac_f32_e32 v44, v141, v141
	v_fmac_f32_e32 v44, v231, v231
	v_fmac_f32_e32 v44, v142, v142
	v_fmac_f32_e32 v44, v232, v232
	v_fmac_f32_e32 v44, v143, v143
	v_fmac_f32_e32 v44, v233, v233
	v_cvt_pk_bf16_f32 v230, v140, v230
	v_cvt_pk_bf16_f32 v231, v141, v231
	v_cvt_pk_bf16_f32 v232, v142, v232
	v_cvt_pk_bf16_f32 v233, v143, v233
	global_store_dwordx4 v189, v[230:233], s[8:9] offset:256
	s_waitcnt vmcnt(14)
	v_add_u32_e32 v189, 0x50000, v188
	v_lshlrev_b32_e32 v140, 16, v234
	v_and_b32_e32 v234, 0xffff0000, v234
	v_lshlrev_b32_e32 v141, 16, v235
	v_and_b32_e32 v235, 0xffff0000, v235
	v_lshlrev_b32_e32 v142, 16, v236
	v_and_b32_e32 v236, 0xffff0000, v236
	v_lshlrev_b32_e32 v143, 16, v237
	v_and_b32_e32 v237, 0xffff0000, v237
	v_fmac_f32_e32 v140, 0.5, v28
	v_fmac_f32_e32 v234, 0.5, v29
	v_fmac_f32_e32 v141, 0.5, v30
	v_fmac_f32_e32 v235, 0.5, v31
	v_fmac_f32_e32 v142, 0.5, v24
	v_fmac_f32_e32 v236, 0.5, v25
	v_fmac_f32_e32 v143, 0.5, v26
	v_fmac_f32_e32 v237, 0.5, v27
	v_mul_f32_e32 v28, v140, v140
	v_fmac_f32_e32 v28, v234, v234
	v_fmac_f32_e32 v28, v141, v141
	v_fmac_f32_e32 v28, v235, v235
	v_fmac_f32_e32 v28, v142, v142
	v_fmac_f32_e32 v28, v236, v236
	v_fmac_f32_e32 v28, v143, v143
	v_fmac_f32_e32 v28, v237, v237
	v_cvt_pk_bf16_f32 v234, v140, v234
	v_cvt_pk_bf16_f32 v235, v141, v235
	v_cvt_pk_bf16_f32 v236, v142, v236
	v_cvt_pk_bf16_f32 v237, v143, v237
	global_store_dwordx4 v189, v[234:237], s[8:9]
	v_lshlrev_b32_e32 v140, 16, v238
	v_and_b32_e32 v238, 0xffff0000, v238
	v_lshlrev_b32_e32 v141, 16, v239
	v_and_b32_e32 v239, 0xffff0000, v239
	v_lshlrev_b32_e32 v142, 16, v240
	v_and_b32_e32 v240, 0xffff0000, v240
	v_lshlrev_b32_e32 v143, 16, v241
	v_and_b32_e32 v241, 0xffff0000, v241
	v_fmac_f32_e32 v140, 0.5, v20
	v_fmac_f32_e32 v238, 0.5, v21
	v_fmac_f32_e32 v141, 0.5, v22
	v_fmac_f32_e32 v239, 0.5, v23
	v_fmac_f32_e32 v142, 0.5, v16
	v_fmac_f32_e32 v240, 0.5, v17
	v_fmac_f32_e32 v143, 0.5, v18
	v_fmac_f32_e32 v241, 0.5, v19
	v_fmac_f32_e32 v28, v140, v140
	v_fmac_f32_e32 v28, v238, v238
	v_fmac_f32_e32 v28, v141, v141
	v_fmac_f32_e32 v28, v239, v239
	v_fmac_f32_e32 v28, v142, v142
	v_fmac_f32_e32 v28, v240, v240
	v_fmac_f32_e32 v28, v143, v143
	v_fmac_f32_e32 v28, v241, v241
	v_cvt_pk_bf16_f32 v238, v140, v238
	v_cvt_pk_bf16_f32 v239, v141, v239
	v_cvt_pk_bf16_f32 v240, v142, v240
	v_cvt_pk_bf16_f32 v241, v143, v241
	global_store_dwordx4 v189, v[238:241], s[8:9] offset:256
	s_waitcnt vmcnt(14)
	v_add_u32_e32 v189, 0x58000, v188
	v_lshlrev_b32_e32 v140, 16, v242
	v_and_b32_e32 v242, 0xffff0000, v242
	v_lshlrev_b32_e32 v141, 16, v243
	v_and_b32_e32 v243, 0xffff0000, v243
	v_lshlrev_b32_e32 v142, 16, v244
	v_and_b32_e32 v244, 0xffff0000, v244
	v_lshlrev_b32_e32 v143, 16, v245
	v_and_b32_e32 v245, 0xffff0000, v245
	v_fmac_f32_e32 v140, 0.5, v12
	v_fmac_f32_e32 v242, 0.5, v13
	v_fmac_f32_e32 v141, 0.5, v14
	v_fmac_f32_e32 v243, 0.5, v15
	v_fmac_f32_e32 v142, 0.5, v8
	v_fmac_f32_e32 v244, 0.5, v9
	v_fmac_f32_e32 v143, 0.5, v10
	v_fmac_f32_e32 v245, 0.5, v11
	v_mul_f32_e32 v12, v140, v140
	v_fmac_f32_e32 v12, v242, v242
	v_fmac_f32_e32 v12, v141, v141
	v_fmac_f32_e32 v12, v243, v243
	v_fmac_f32_e32 v12, v142, v142
	v_fmac_f32_e32 v12, v244, v244
	v_fmac_f32_e32 v12, v143, v143
	v_fmac_f32_e32 v12, v245, v245
	v_cvt_pk_bf16_f32 v242, v140, v242
	v_cvt_pk_bf16_f32 v243, v141, v243
	v_cvt_pk_bf16_f32 v244, v142, v244
	v_cvt_pk_bf16_f32 v245, v143, v245
	global_store_dwordx4 v189, v[242:245], s[8:9]
	v_lshlrev_b32_e32 v140, 16, v246
	v_and_b32_e32 v246, 0xffff0000, v246
	v_lshlrev_b32_e32 v141, 16, v247
	v_and_b32_e32 v247, 0xffff0000, v247
	v_lshlrev_b32_e32 v142, 16, v248
	v_and_b32_e32 v248, 0xffff0000, v248
	v_lshlrev_b32_e32 v143, 16, v249
	v_and_b32_e32 v249, 0xffff0000, v249
	v_fmac_f32_e32 v140, 0.5, v4
	v_fmac_f32_e32 v246, 0.5, v5
	v_fmac_f32_e32 v141, 0.5, v6
	v_fmac_f32_e32 v247, 0.5, v7
	v_fmac_f32_e32 v142, 0.5, v0
	v_fmac_f32_e32 v248, 0.5, v1
	v_fmac_f32_e32 v143, 0.5, v2
	v_fmac_f32_e32 v249, 0.5, v3
	v_fmac_f32_e32 v12, v140, v140
	v_fmac_f32_e32 v12, v246, v246
	v_fmac_f32_e32 v12, v141, v141
	v_fmac_f32_e32 v12, v247, v247
	v_fmac_f32_e32 v12, v142, v142
	v_fmac_f32_e32 v12, v248, v248
	v_fmac_f32_e32 v12, v143, v143
	v_fmac_f32_e32 v12, v249, v249
	v_cvt_pk_bf16_f32 v246, v140, v246
	v_cvt_pk_bf16_f32 v247, v141, v247
	v_cvt_pk_bf16_f32 v248, v142, v248
	v_cvt_pk_bf16_f32 v249, v143, v249
	global_store_dwordx4 v189, v[246:249], s[8:9] offset:256
	v_and_b32_e32 v143, 64, v220
	v_xor_b32_e32 v140, 16, v220
	v_add_u32_e32 v143, 64, v143
	v_cmp_lt_i32_e32 vcc, v140, v143
	v_xor_b32_e32 v141, 32, v220
	s_nop 1
	v_cndmask_b32_e32 v140, v220, v140, vcc
	v_lshlrev_b32_e32 v140, 2, v140
	v_cmp_lt_i32_e32 vcc, v141, v143
	s_nop 1
	v_cndmask_b32_e32 v141, v220, v141, vcc
	v_lshlrev_b32_e32 v141, 2, v141
	ds_bpermute_b32 v127, v140, v126
	ds_bpermute_b32 v109, v140, v108
	ds_bpermute_b32 v93, v140, v92
	ds_bpermute_b32 v77, v140, v76
	ds_bpermute_b32 v61, v140, v60
	ds_bpermute_b32 v45, v140, v44
	ds_bpermute_b32 v29, v140, v28
	ds_bpermute_b32 v13, v140, v12
	v_lshl_add_u32 v212, s47, 8, v144
	v_ashrrev_i32_e32 v213, 31, v212
	v_lshlrev_b64 v[212:213], 6, v[212:213]
	v_lshl_add_u64 v[212:213], s[10:11], 0, v[212:213]
	v_lshl_add_u64 v[212:213], s[16:17], 2, v[212:213]
	s_lshl_b32 s92, s38, 2
	v_lshl_add_u64 v[212:213], v[212:213], 0, s[92:93]
	v_add_co_u32_e32 v188, vcc, 0x2000, v212
	s_nop 1
	v_addc_co_u32_e32 v189, vcc, 0, v213, vcc
	s_waitcnt lgkmcnt(0)
	v_add_f32_e32 v126, v126, v127
	v_add_f32_e32 v108, v108, v109
	v_add_f32_e32 v92, v92, v93
	v_add_f32_e32 v76, v76, v77
	v_add_f32_e32 v60, v60, v61
	v_add_f32_e32 v44, v44, v45
	v_add_f32_e32 v28, v28, v29
	v_add_f32_e32 v12, v12, v13
	ds_bpermute_b32 v127, v141, v126
	ds_bpermute_b32 v109, v141, v108
	ds_bpermute_b32 v93, v141, v92
	ds_bpermute_b32 v77, v141, v76
	ds_bpermute_b32 v61, v141, v60
	ds_bpermute_b32 v45, v141, v44
	ds_bpermute_b32 v29, v141, v28
	ds_bpermute_b32 v13, v141, v12
	s_waitcnt lgkmcnt(0)
	v_add_f32_e32 v126, v126, v127
	v_add_f32_e32 v108, v108, v109
	v_add_f32_e32 v92, v92, v93
	v_add_f32_e32 v76, v76, v77
	v_add_f32_e32 v60, v60, v61
	v_add_f32_e32 v44, v44, v45
	v_add_f32_e32 v28, v28, v29
	v_add_f32_e32 v12, v12, v13
	s_and_saveexec_b64 s[18:19], s[2:3]
	global_store_dword v[212:213], v126, off
	global_store_dword v[212:213], v108, off offset:1024
	global_store_dword v[212:213], v92, off offset:2048
	global_store_dword v[212:213], v76, off offset:3072
	global_store_dword v[188:189], v60, off
	global_store_dword v[188:189], v44, off offset:1024
	global_store_dword v[188:189], v28, off offset:2048
	global_store_dword v[188:189], v12, off offset:3072
	s_or_b64 exec, exec, s[18:19]
	s_and_b64 vcc, exec, s[4:5]
	s_mov_b64 s[4:5], -1
	s_cbranch_vccnz .LBB0_1125
	s_andn2_b64 vcc, exec, s[6:7]
	s_cbranch_vccnz .LBB0_1124
	s_barrier
	s_branch .LBB0_1124
